# in-proj: slack workgroups in two convoys one third and two thirds of a tile late (three evenly spaced groups with the critical one)
# baseline (speedup 1.0000x reference)
; __device__ __forceinline__ int opaque_tid() { int t = threadIdx.x; asm volatile("" : "+v"(t)); return t; }
; template <class Epi, class Sched>
; __device__ __forceinline__ void gemm_phase(LAS unsigned char* lds, const Gemm g, const Sched& S, const Epi& E) {
;     const int tid = opaque_tid(), wid = __builtin_amdgcn_readfirstlane(tid >> 6), lane = tid & 63, wr = wid >> 2, wc = wid & 3, fr = lane & 15, fq = lane >> 4;
;     const int K = g.K, nt = K / BK;
;     unsigned voffA[2], voffB[2];
; #pragma unroll
;     for (int i = 0; i < 2; ++i) { int R, C; stage_rc(tid * 16 + i * 8192, R, C); const int Rb = Epi::PERM ? ((R & ~31) + perm32(R & 31)) : R;
;         voffA[i] = (unsigned)(R * K + C) * 2u; voffB[i] = (unsigned)(Rb * K + C) * 2u; }
;     ...
;     if (!S.next(0, cur)) return;
.LBB0_180:
	s_or_b64 exec, exec, s[0:1]
	v_readlane_b32 s0, v240, 24
	v_readlane_b32 s1, v240, 25
	s_mov_b32 s1, s3
	v_writelane_b32 v240, s0, 24
	s_waitcnt lgkmcnt(0)
	v_mov_b32_e32 v0, v135
	v_writelane_b32 v240, s1, 25
	v_readlane_b32 s0, v243, 39
	v_readlane_b32 s1, v243, 40
	s_barrier
	s_andn2_b64 vcc, exec, s[0:1]
	v_readfirstlane_b32 s5, v0
	s_cbranch_vccnz .LBB0_192
	v_lshlrev_b32_e32 v4, 4, v0
	v_add_u32_e32 v2, 0x2000, v4
	v_ashrrev_i32_e32 v1, 31, v2
	v_lshrrev_b32_e32 v1, 22, v1
	v_add_u32_e32 v1, v2, v1
	v_ashrrev_i32_e32 v1, 10, v1
	v_mul_i32_i24_e32 v3, 0x400, v1
	v_sub_u32_e32 v2, v2, v3
	v_lshrrev_b32_e32 v3, 4, v2
	v_bitop3_b32 v3, v3, v2, 32 bitop3:0x6c
	v_ashrrev_i32_e32 v2, 31, v3
	v_lshrrev_b32_e32 v2, 26, v2
	v_add_u32_e32 v5, v3, v2
	v_lshlrev_b32_e32 v6, 3, v1
	v_ashrrev_i32_e32 v2, 6, v5
	v_and_b32_e32 v6, -16, v6
	v_add_u32_e32 v6, v2, v6
	v_and_b32_e32 v7, 3, v2
	s_mov_b32 s2, 0x1fffe0
	v_lshrrev_b32_e32 v9, 2, v6
	v_lshlrev_b32_e32 v10, 1, v6
	v_and_b32_e32 v5, 0xc0, v5
	v_and_or_b32 v7, v6, s2, v7
	v_and_b32_e32 v9, 4, v9
	v_and_b32_e32 v10, 24, v10
	v_sub_u32_e32 v3, v3, v5
	v_or3_b32 v7, v7, v9, v10
	v_lshlrev_b32_e32 v9, 5, v1
	v_ashrrev_i16_sdwa v3, v176, sext(v3) dst_sel:DWORD dst_unused:UNUSED_PAD src0_sel:DWORD src1_sel:BYTE_0
	v_and_b32_e32 v9, 32, v9
	v_bfe_i32 v3, v3, 0, 16
	v_add_lshl_u32 v5, v9, v3, 1
	v_lshl_add_u32 v140, v7, 11, v5
	v_lshl_add_u32 v142, v6, 11, v5
	v_bfe_i32 v5, v0, 27, 1
	v_lshrrev_b32_e32 v5, 22, v5
	v_add_u32_e32 v5, v4, v5
	v_and_b32_e32 v5, 0xfffffc00, v5
	v_sub_u32_e32 v4, v4, v5
	v_lshrrev_b32_e32 v5, 4, v4
	v_bitop3_b32 v6, v5, v4, 32 bitop3:0x6c
	v_ashrrev_i32_e32 v5, 31, v0
	v_lshrrev_b32_e32 v5, 26, v5
	v_ashrrev_i32_e32 v4, 31, v4
	v_add_u32_e32 v5, v0, v5
	v_lshrrev_b32_e32 v4, 26, v4
	v_ashrrev_i32_e32 v5, 6, v5
	v_add_u32_e32 v4, v6, v4
	v_lshlrev_b32_e32 v7, 3, v5
	v_ashrrev_i32_e32 v4, 6, v4
	v_and_b32_e32 v7, -16, v7
	v_add_u32_e32 v7, v4, v7
	v_readlane_b32 s0, v240, 24
	v_and_b32_e32 v9, 3, v4
	v_lshrrev_b32_e32 v10, 2, v7
	v_lshlrev_b32_e32 v11, 1, v7
	s_mul_i32 s0, s0, 0x700000
	v_and_or_b32 v9, v7, s2, v9
	v_and_b32_e32 v10, 4, v10
	v_and_b32_e32 v11, 24, v11
	v_readlane_b32 s1, v240, 25
	s_add_u32 s6, s62, s0
	v_or3_b32 v9, v9, v10, v11
	v_mul_i32_i24_e32 v11, 64, v4
	s_addc_u32 s7, s63, 0
	s_ashr_i32 s1, s5, 6
	v_sub_u32_e32 v6, v6, v11
	s_ashr_i32 s0, s5, 8
	s_lshl_b32 s8, s1, 10
	v_lshlrev_b32_e32 v10, 5, v5
	v_ashrrev_i16_sdwa v6, v176, sext(v6) dst_sel:DWORD dst_unused:UNUSED_PAD src0_sel:DWORD src1_sel:BYTE_0
	v_readlane_b32 s10, v241, 18
	v_and_b32_e32 v10, 32, v10
	v_bfe_i32 v6, v6, 0, 16
	v_readlane_b32 s11, v241, 19
	s_add_u32 s66, s6, s10
	v_add_lshl_u32 v10, v10, v6, 1
	s_addc_u32 s67, s7, s11
	s_add_i32 s9, s8, 16
	v_lshl_add_u32 v144, v9, 11, v10
	s_cmp_lt_u32 s92, 0x70
	s_cbranch_scc1 .Lds184_x
	s_cmp_lg_u32 s46, 0x100
	s_cbranch_scc1 .Lds184_x
	s_sub_u32 s98, s92, 0x70
	s_cmp_lt_u32 s98, 72
	s_cselect_b32 s98, 7, 14
	s_min_u32 s98, s98, 20
